# copyshare2: layer-1 weight copies spread over all 256 CUs in layer 0's in-projection phase (CUs 32..223 one 16-item share, 224..255 w_in+w_kv of a virtual CU, chain CUs 0..31 its w_out); nobody takes
# baseline (speedup 1.0000x reference)
; #define LAS __attribute__((address_space(3)))
; #define P (*({ CParams* q_ = kp; asm volatile("" : "+s"(q_)); q_; }))
; #define wave (__builtin_amdgcn_readfirstlane(tid >> 6))
; DI void ret_unit(CParams& P, int l, int u, LAS unsigned char* lds, int tid_, int lane_, int wave_) {
;     ...
;     const int hh = u & 3, b = u >> 2;
;     constexpr int LD = 264, LDP = 72, LDR = 256, IMG = 33792;
;     LAS bf16_t* Qs = (LAS bf16_t*)lds; LAS bf16_t* Ks = (LAS bf16_t*)(lds + IMG); LAS bf16_t* Vs = (LAS bf16_t*)(lds + 2 * IMG);
;     LAS bf16_t* Ps = (LAS bf16_t*)(lds + 3 * IMG); LAS bf16_t* R = (LAS bf16_t*)(lds + 3 * IMG + 9216);
;     const float g64 = exp2f(64.f * log2f(1.f - exp2f(-5.f - (float)hh)));
; __global__ void __launch_bounds__(NTHREADS, 2) fwd_megakernel(Params P_) {
;     ...
;         const float* rss_in = (const float*)(ws + (l == 0 ? WS_RSS0 : WS_RSS1));
;         float* rss_out = (float*)(ws + (l == 0 ? WS_RSS1 : WS_RSS2));
;         const pg8::Gemm g_in{(const bf16_t*)(ws + WS_XB), (const bf16_t*)(ws + WS_WIN) + (size_t)l * NPROJ * DM, MTOK, NPROJ, DM};
;         const pg8::EpiProj E_in{(bf16_t*)(ws + WS_PROJ), NPROJ, rss_in, 1.f / DM, EPS, 1, (const float*)(ws + WS_COS), (const float*)(ws + WS_SIN), (float*)(ws + WS_AVSTAT) + (size_t)l * MTOK * 2};
;         { const pg8::SubOrder S{16, 1024, 16, 24, 24, bx, G, 0};
;           pg8::gemm_phase<pg8::EpiProj, pg8::SubOrder, true, true>(lds, g_in, S, E_in); }
;         xcd_barrier(xbar);
;     ...
;         if (bx < 32) ret_unit(P, l, bx, lds, tid, lane, wave);
;     ...
;         { const pg8::SubOrder S{32, 2048, 24, 0, 16, bx, G, 1};
;           pg8::gemm_phase<pg8::EpiProj, pg8::SubOrder, true, true>(lds, g_in, S, E_in); }
;         { pg8::Gemm g{(const bf16_t*)(ws + WS_MEMB), (const bf16_t*)(ws + WS_WKV) + (size_t)l * NKV * DM, MROWS, NKV, DM}; pg8::StaticOrder S; S.init(MROWS, NKV, G, (bx >= 96 && bx < 160) ? bx - 96 : (1 << 20));
.LBB0_248:
	v_writelane_b32 v254, s42, 3
	s_nop 1
	v_writelane_b32 v254, s43, 4
	s_or_b64 exec, exec, s[38:39]
	s_add_u32 s50, s72, 0x12200000
	s_addc_u32 s51, s73, 0
	s_add_u32 s80, s72, 0x200000
	s_addc_u32 s83, s73, 0
	s_add_u32 s52, s72, 0x1a200000
	s_addc_u32 s53, s73, 0
	s_add_u32 s0, s72, 0x3ba00000
	s_addc_u32 s1, s73, 0
	v_writelane_b32 v254, s0, 5
	s_mov_b32 s33, 0xc2fc0000
	v_mov_b32_e32 v219, 0x42800000
	v_writelane_b32 v254, s1, 6
	s_add_u32 s0, s72, 0x3c200000
	s_addc_u32 s1, s73, 0
	s_add_u32 s88, s72, 0x40000
	s_addc_u32 s89, s73, 0
	s_cmpk_lt_i32 s69, 0x400
	v_writelane_b32 v254, s0, 7
	s_cselect_b64 s[8:9], -1, 0
	s_ashr_i32 s92, s69, 31
	v_writelane_b32 v254, s1, 8
	s_lshr_b32 s0, s92, 29
	s_add_i32 s2, s69, s0
	s_ashr_i32 s4, s2, 3
	s_lshl_b32 s0, s69, 7
	s_mul_i32 s1, s4, 0xfffffc01
	s_add_i32 s0, s1, s0
	s_ashr_i32 s1, s0, 31
	s_lshr_b32 s1, s1, 25
	s_add_i32 s1, s0, s1
	s_ashr_i32 s5, s1, 7
	s_and_b32 s1, s1, 0xffffff80
	s_sub_i32 s0, s0, s1
	s_bfe_i32 s1, s0, 0x80000
	s_bfe_u32 s1, s1, 0x3000c
	s_add_i32 s1, s0, s1
	s_bfe_i32 s6, s1, 0x80000
	s_and_b32 s6, 0xffff, s6
	s_and_b32 s1, s1, 0xf8
	s_lshr_b32 s6, s6, 3
	s_sub_i32 s0, s0, s1
	s_lshl_b32 s5, s5, 3
	s_sext_i32_i8 s0, s0
	s_add_i32 s6, s6, 24
	s_add_i32 s10, s5, s0
	s_and_b32 s6, s6, 0xff
	s_cmp_lt_i32 s69, 32
	s_cselect_b64 s[0:1], -1, 0
	s_and_b32 s5, s69, 3
	v_cvt_f32_ubyte0_e32 v0, s5
	v_sub_f32_e32 v0, 0xc0a00000, v0
	v_cmp_gt_f32_e32 vcc, s33, v0
	v_writelane_b32 v254, s0, 9
	s_mov_b32 s45, 0x800000
	v_cndmask_b32_e32 v1, 0, v219, vcc
	v_add_f32_e32 v0, v0, v1
	v_exp_f32_e32 v0, v0
	v_writelane_b32 v254, s1, 10
	s_and_b64 s[0:1], vcc, exec
	s_cselect_b32 s0, 0xffffffc0, 0
	v_ldexp_f32 v0, v0, s0
	v_sub_f32_e32 v0, 1.0, v0
	v_cmp_gt_f32_e32 vcc, s45, v0
	s_and_b64 s[0:1], vcc, exec
	s_cselect_b32 s0, 32, 0
	v_ldexp_f32 v0, v0, s0
	v_log_f32_e32 v0, v0
	v_mov_b32_e32 v220, 0x42000000
	v_cndmask_b32_e32 v1, 0, v220, vcc
	s_mul_i32 s0, s77, s76
	v_sub_f32_e32 v0, v0, v1
	v_mul_f32_e32 v1, 0x42800000, v0
	v_cmp_gt_f32_e32 vcc, s33, v1
	s_lshl_b32 s7, s5, 8
	s_mul_i32 s77, s0, s3
	v_cndmask_b32_e32 v1, 0, v219, vcc
	v_fmac_f32_e32 v1, 0x42800000, v0
	v_exp_f32_e32 v0, v1
	s_and_b64 s[0:1], vcc, exec
	s_cselect_b32 s0, 0xffffffc0, 0
	s_mov_b32 s97, 0
	v_ldexp_f32 v192, v0, s0
	s_lshl_b32 s0, s69, 9
	s_and_b32 s0, s0, 0xfffff800
	v_writelane_b32 v254, s0, 11
	s_cmp_gt_i32 s69, 31
	s_movk_i32 s0, 0xffe0
	s_cselect_b32 s0, s0, 0x700
	s_add_i32 s0, s0, s69
	s_ashr_i32 s1, s0, 31
	s_lshr_b32 s1, s1, 29
	s_add_i32 s1, s0, s1
	s_ashr_i32 s1, s1, 3
	s_lshl_b32 s0, s0, 8
	s_mulk_i32 s1, 0xf801
	s_add_i32 s0, s1, s0
	s_ashr_i32 s1, s0, 31
	s_lshr_b32 s1, s1, 24
	s_add_i32 s1, s0, s1
	s_ashr_i32 s3, s1, 8
	s_and_b32 s1, s1, 0xffffff00
	s_sub_i32 s0, s0, s1
	s_bfe_u32 s1, s0, 0x3001c
	s_add_i32 s1, s0, s1
	s_sext_i32_i16 s5, s1
	s_and_b32 s1, s1, 0xfff8
	s_sub_i32 s1, s0, s1
	s_lshl_b32 s3, s3, 3
	s_sext_i32_i16 s1, s1
	s_ashr_i32 s5, s5, 3
	s_add_i32 s12, s3, s1
	s_cmpk_lt_i32 s0, 0xc0
	s_cselect_b32 s0, 0, 16
	s_add_i32 s14, s0, s5
	s_mov_b32 s0, s12
	s_ashr_i32 s13, s12, 31
	v_writelane_b32 v254, s0, 12
	s_ashr_i32 s15, s14, 31
	v_mov_b32_e32 v0, 0x60
	v_writelane_b32 v254, s1, 13
	s_lshl_b64 s[0:1], s[12:13], 21
	s_mov_b32 s12, s14
	v_writelane_b32 v254, s12, 14
	s_movk_i32 s55, 0x6000
	v_mov_b32_e32 v194, v192
	v_writelane_b32 v254, s13, 15
	s_lshl_b64 s[12:13], s[14:15], 21
	v_writelane_b32 v254, s12, 16
	s_add_u32 s0, s50, s0
	s_addc_u32 s1, s51, s1
	v_writelane_b32 v254, s13, 17
	s_add_u32 s12, s0, 0x100000
	v_writelane_b32 v254, s0, 18
	s_addc_u32 s13, s1, 0
	v_mov_b32_e32 v195, v192
	v_writelane_b32 v254, s1, 19
	v_writelane_b32 v254, s12, 20
	s_add_i32 s0, s69, 0x700
	s_movk_i32 s81, 0x2000
	v_writelane_b32 v254, s13, 21
	v_writelane_b32 v254, s0, 22
	v_sub_co_u32_e64 v0, s[0:1], s69, v0
	s_nop 0
	v_readfirstlane_b32 s3, v0
	v_writelane_b32 v254, s0, 23
	v_mov_b32_e32 v197, 0
	v_mov_b32_e32 v222, 0x358637bd
	v_writelane_b32 v254, s1, 24
	s_add_i32 s0, s69, 0x7a0
	v_writelane_b32 v254, s0, 25
	s_sub_i32 s0, s69, 32
	s_add_u32 s5, s72, 0x3a200000
	s_addc_u32 s11, s73, 0
	v_writelane_b32 v254, s0, 26
	s_add_u32 s0, s72, 0x10200000
	v_writelane_b32 v254, s0, 27
	s_addc_u32 s0, s73, 0
	s_cmp_lt_u32 s3, 64
	v_writelane_b32 v254, s0, 28
	s_cselect_b64 s[0:1], -1, 0
	v_writelane_b32 v254, s0, 29
; #define P (*({ CParams* q_ = kp; asm volatile("" : "+s"(q_)); q_; }))
; __global__ void __launch_bounds__(NTHREADS, 2) fwd_megakernel(Params P_) {
;     ...
;         { pg8::Gemm g{(const bf16_t*)(ws + WS_MEMB), (const bf16_t*)(ws + WS_WKV) + (size_t)l * NKV * DM, MROWS, NKV, DM}; pg8::StaticOrder S; S.init(MROWS, NKV, G, (bx >= 96 && bx < 160) ? bx - 96 : (1 << 20));
;           pg8::EpiProj E{(bf16_t*)(ws + WS_KV), NKV, nullptr, 0.f, 0.f, 0, nullptr, nullptr, nullptr};
;           pg8::gemm_phase<pg8::EpiProj, pg8::StaticOrder, true, true>(lds, g, S, E); }
;         if (bx >= 160) { int t2 = threadIdx.x; asm volatile("" : "+v"(t2)); const int w2 = __builtin_amdgcn_readfirstlane(t2 >> 6);
;             convert_weights(P, 1, lds, (bx - 160) * NWAVES + w2, 96 * NWAVES, t2 & 63, w2, l == 0 ? 5 : 2); }
	v_mov_b32_e32 v223, 1
	s_mov_b32 s84, 0x3e0f83e1
	v_writelane_b32 v254, s1, 30
	s_and_b64 s[0:1], s[0:1], exec
	s_cselect_b32 s1, s3, 0x100000
	s_add_u32 s12, s72, 0x3b200000
	s_addc_u32 s13, s73, 0
	v_writelane_b32 v254, s12, 31
	s_bfe_u32 s3, s1, 0x30003
	s_lshr_b32 s0, s1, 3
	v_writelane_b32 v254, s13, 32
	v_writelane_b32 v254, s3, 33
	v_writelane_b32 v254, s1, 34
	s_and_b32 s1, s1, 7
	v_writelane_b32 v254, s1, 35
	s_lshl_b32 s1, s1, 21
	s_lshl_b32 s0, s0, 21
	v_writelane_b32 v254, s1, 36
	v_writelane_b32 v254, s5, 37
	s_add_u32 s0, s5, s0
	v_writelane_b32 v254, s11, 38
	s_addc_u32 s1, s11, 0
	s_add_u32 s12, s0, 0x100000
	v_writelane_b32 v254, s0, 39
	s_addc_u32 s13, s1, 0
	s_movk_i32 s85, 0xffdf
	v_writelane_b32 v254, s1, 40
	v_writelane_b32 v254, s12, 41
	s_ashr_i32 s0, s76, 31
	s_cmpk_gt_i32 s69, 0xffff
	v_writelane_b32 v254, s13, 42
	v_writelane_b32 v254, s0, 43
	s_cselect_b64 s[0:1], -1, 0
	v_writelane_b32 v254, s0, 44
	v_mov_b32_e32 v224, 0x3d800000
	v_not_b32_e32 v225, 63
	v_writelane_b32 v254, s1, 45
	s_add_i32 s0, s69, 0xffffffe0
	s_and_b32 s0, s0, 63
	s_add_i32 s98, s69, 0xffffff60
	s_cmpk_gt_i32 s69, 0xdf
	s_cselect_b32 s0, s98, s0
	s_add_i32 s98, s69, 64
	s_cmpk_lt_i32 s69, 0x20
	s_cselect_b32 s0, s98, s0
	s_lshl_b32 s0, s0, 3
	s_add_u32 s5, s72, 0x32200000
	s_addc_u32 s12, s73, 0
	v_writelane_b32 v254, s0, 46
	s_add_u32 s0, s72, 0xc200000
	v_writelane_b32 v254, s0, 47
	s_addc_u32 s0, s73, 0
	v_writelane_b32 v254, s0, 48
	s_and_b32 s0, s2, -8
	s_sub_i32 s2, s69, s0
	s_mov_b32 s0, s10
	v_writelane_b32 v254, s0, 49
	s_ashr_i32 s11, s10, 31
	s_lshl_b32 s3, s2, 7
	v_writelane_b32 v254, s1, 50
	s_lshl_b64 s[0:1], s[10:11], 21
	v_writelane_b32 v254, s6, 51
	s_lshl_b32 s6, s6, 21
	s_add_u32 s0, s50, s0
	s_addc_u32 s1, s51, s1
	v_writelane_b32 v254, s6, 52
	s_add_u32 s10, s0, 0x100000
	v_writelane_b32 v254, s0, 53
	s_addc_u32 s11, s1, 0
	s_cmp_lt_i32 s2, 0
	s_mulk_i32 s2, 0x81
	v_writelane_b32 v254, s1, 54
	s_cselect_b32 s0, s2, s3
	s_add_i32 s0, s0, s4
	s_ashr_i32 s1, s0, 31
	s_lshr_b32 s1, s1, 25
	s_add_i32 s1, s0, s1
	s_ashr_i32 s2, s1, 7
	s_and_b32 s1, s1, 0xff80
	s_sub_i32 s1, s0, s1
	s_bfe_i32 s0, s1, 0x80000
	s_bfe_u32 s0, s0, 0x3000c
	s_add_i32 s3, s1, s0
	s_bfe_i32 s0, s3, 0x80000
	s_and_b32 s3, s3, 0xf8
	s_sub_i32 s1, s1, s3
	v_writelane_b32 v254, s10, 55
	s_lshl_b32 s2, s2, 3
	s_sext_i32_i16 s4, s0
	s_sext_i32_i8 s1, s1
	v_writelane_b32 v254, s11, 56
	s_add_i32 s10, s2, s1
	s_ashr_i32 s1, s4, 3
	s_lshr_b32 s0, s4, 3
	v_writelane_b32 v254, s1, 57
	s_mov_b32 s2, s10
	v_writelane_b32 v254, s2, 58
	s_bfe_i64 s[0:1], s[0:1], 0x100000
	s_ashr_i32 s11, s10, 31
	v_writelane_b32 v254, s3, 59
	s_lshl_b64 s[0:1], s[0:1], 21
	s_lshl_b64 s[2:3], s[10:11], 21
	v_writelane_b32 v254, s0, 60
	v_mbcnt_hi_u32_b32 v226, -1, v71
	v_mov_b32_e32 v227, 0x840
	v_writelane_b32 v254, s1, 61
	s_add_u32 s0, s5, s2
	s_addc_u32 s1, s12, s3
	s_add_u32 s2, s0, 0x100000
	v_writelane_b32 v255, s0, 0
	s_addc_u32 s3, s1, 0
	v_writelane_b32 v254, s5, 62
	v_writelane_b32 v255, s1, 1
	v_writelane_b32 v255, s2, 2
	s_add_i32 s0, 0, 0x27f20
	v_writelane_b32 v254, s12, 63
	v_writelane_b32 v255, s3, 3
	v_writelane_b32 v255, s8, 4
	s_movk_i32 s93, 0x210
	s_movk_i32 s79, 0x7fff
	v_writelane_b32 v255, s9, 5
	v_writelane_b32 v255, s0, 6
	s_add_i32 s0, 0, 0x27f24
	v_writelane_b32 v255, s0, 7
	s_add_i32 s0, 0, 0x1b000
	v_writelane_b32 v255, s0, 8
	s_add_i32 s0, 0, 0x18c00
	v_writelane_b32 v255, s0, 9
	v_writelane_b32 v255, s7, 10
	v_writelane_b32 v255, s72, 11
	v_cndmask_b32_e64 v221, 0, 1, s[8:9]
	s_lshl_b32 s16, s7, 1
	v_writelane_b32 v255, s73, 12
	v_writelane_b32 v255, s74, 13
	s_mov_b32 s57, 0x32201000
	s_movk_i32 s43, 0x1000
	v_writelane_b32 v255, s75, 14
	v_writelane_b32 v255, s69, 15
	v_writelane_b32 v255, s76, 16
	s_mov_b32 s70, 0x1a202000
	s_mov_b32 s71, 0x32200000
	v_writelane_b32 v255, s77, 17
	v_writelane_b32 v255, s78, 18
	v_writelane_b32 v255, s86, 19
	s_movk_i32 s56, 0x110
	s_add_i32 s4, 0, 0x11000
	v_writelane_b32 v255, s87, 20
	v_writelane_b32 v255, s80, 21
	v_writelane_b32 v255, s83, 22
	v_writelane_b32 v255, s88, 23
	v_writelane_b32 v255, s89, 24
	v_writelane_b32 v255, s92, 25
	s_movk_i32 s5, 0x5000
	s_mov_b64 s[0:1], -1
	s_mov_b64 s[60:61], 0x80
	s_mov_b32 s82, 0x3a800000
	s_mov_b32 s62, s97
	v_writelane_b32 v255, s77, 26
	s_waitcnt lgkmcnt(0)
	s_barrier
	s_branch .LBB0_251

; #define LAS __attribute__((address_space(3)))
; #define P (*({ CParams* q_ = kp; asm volatile("" : "+s"(q_)); q_; }))
; #define wave (__builtin_amdgcn_readfirstlane(tid >> 6))
;     unsigned char* ws = P.ws;
;     LAS float* scr = (LAS float*)(lds + wave * 16384);
;     constexpr int I_IN = (DM / 64) * (NPROJ / 32), I_OUT = (DM / 64) * (DM / 32), I_KV = (DM / 64) * (NKV / 32);
;     if (which & 1) p0_matrix(P.w_in + (size_t)l * DM * NPROJ, P.norm_g + l * DM, DM, NPROJ, (bf16_t*)(ws + WS_WIN) + (size_t)l * NPROJ * DM, scr, I_IN, gw, NGW, lane);
;     if (which & 2) p0_matrix(P.w_out + (size_t)l * DM * DM, nullptr, DM, DM, (bf16_t*)(ws + WS_WOUT) + (size_t)l * DM * DM, scr, I_OUT, gw, NGW, lane);
;     if (which & 4) p0_matrix(P.w_kv + (size_t)l * DM * NKV, P.mem_ng + l * DM, DM, NKV, (bf16_t*)(ws + WS_WKV) + (size_t)l * NKV * DM, scr, I_KV, gw, NGW, lane);
; __global__ void __launch_bounds__(NTHREADS, 2) fwd_megakernel(Params P_) {
;     ...
;         if (bx >= 160) { int t2 = threadIdx.x; asm volatile("" : "+v"(t2)); const int w2 = __builtin_amdgcn_readfirstlane(t2 >> 6);
;             convert_weights(P, 1, lds, (bx - 160) * NWAVES + w2, 96 * NWAVES, t2 & 63, w2, l == 0 ? 5 : 2); }
.LBB0_517:
	v_readlane_b32 s0, v254, 44
	v_readlane_b32 s1, v254, 45
	s_andn2_b64 vcc, exec, s[0:1]
	s_cbranch_vccnz .LBB0_693
	v_mov_b32_e32 v0, v218
	s_mov_b64 s[12:13], s[74:75]
	v_readfirstlane_b32 s0, v0
	s_ashr_i32 s2, s0, 6
	v_readlane_b32 s0, v254, 46
	s_add_i32 s6, s0, s2
	s_load_dwordx2 s[10:11], s[12:13], 0xa0
	s_and_b64 s[0:1], s[94:95], exec
	s_cselect_b32 s1, 7, 0
	s_mov_b32 s98, 0
	s_movk_i32 s99, 0x5400
	s_cmpk_gt_i32 s69, 0xdf
	s_cbranch_scc0 .Lcopy_cls_lo
	s_and_b32 s1, s1, 5
	s_branch .Lcopy_cls_done
.Lcopy_cls_lo:
	s_cmpk_lt_i32 s69, 0x20
	s_cbranch_scc0 .Lcopy_cls_mid
	s_and_b32 s1, s1, 2
	s_branch .Lcopy_cls_done
.Lcopy_cls_mid:
	s_cmpk_gt_i32 s69, 0x9f
	s_cbranch_scc0 .Lcopy_cls_in
	s_and_b32 s1, s1, 6
	s_branch .Lcopy_cls_done
